# attn: V rows staged with key bits 2,3 un-swapped so P fragments need no permlane32_swap (8 fewer VALU per tile)
# speedup vs baseline: 1.0390x; 1.0018x over previous
; #define LAS __attribute__((address_space(3)))
; __device__ __forceinline__ int v_st(int k, int c) { const int kk = (k & ~0xC) | ((k & 4) << 1) | ((k & 8) >> 1); return ((kk >> 3) * 4 + (c >> 5)) * 512 + ((kk & 7) * 32 + (c & 31)) * 2; }
; __device__ __forceinline__ int v_rd_base(int lane) { return ((lane & 3) << 3) | (((lane >> 2) & 3) << 6) | (((lane >> 4) & 1) << 5) | (((lane >> 5) & 1) << 8); }
; #define SLOAD(i, t) do { const long k0_ = KROW(t); sg[i].a0 = *(const bf16x8*)(KVh + (k0_ + sr) * 1024 + sc); sg[i].a1 = *(const bf16x8*)(KVh + (k0_ + 32 + sr) * 1024 + sc); \
;     sg[i].rp = *(const bf16x8*)(KR + (k0_ + rr) * 32 + rc); } while (0)
; #define SWRITE_AT(boff, i) do { *(LAS bf16x8*)(lds + (boff) + st0) = sg[i].a0; *(LAS bf16x8*)(lds + (boff) + st1) = sg[i].a1; *(LAS bf16x8*)(lds + (boff) + st2) = sg[i].rp; } while (0)
; __device__ __forceinline__ void attn_unit(const bf16_t* __restrict__ Qb, bool rope_q, int tq0, const bf16_t* __restrict__ KVh, const bf16_t* __restrict__ KR,
;                                           int ctx_row0, int lat_row0, int NT, bf16_t* __restrict__ Ob, LAS unsigned char* lds, int wave_s) {
;     ...
;   const int sr = tid >> 4, sc = (tid & 15) * 8, rr = (tid & 255) >> 2, rc = (tid & 3) * 8;
;   const int st0 = (sc < 64) ? OFF_K + KSWZ(sr, sc * 2) : OFF_V + v_st(sr, sc - 64);
;   const int st1 = (sc < 64) ? OFF_K + KSWZ(32 + sr, sc * 2) : OFF_V + v_st(32 + sr, sc - 64);
;   const int st2 = OFF_K + KSWZ(rr, (64 + rc) * 2);
;   const int vb0 = (int)(size_t)(lds + OFF_V) + v_rd_base(lane);
;   struct { bf16x8 a0, a1, rp; } sg[2];
;     ...
;   const int trail = (wave_s >= 4) ? 1 : 0;
;   const LAS unsigned char* Kb = lds + OFF_K;
;   f32x16 p0, p1; float alpha; bf16x8 pa0, pa1, pa2, pa3;
;   SLOAD(0, 0); SLOAD(1, 1);
;   asm volatile("s_waitcnt vmcnt(3)" ::: "memory"); SWRITE_AT(0, 0);
;   if (trail) { asm volatile("s_waitcnt vmcnt(0)" ::: "memory"); SWRITE_AT(BUFB, 1); SLOAD(1, 2); SLOAD(0, 3); }
;   else { SLOAD(0, 2); }
;   __syncthreads();
;   if (trail) __syncthreads();
.LBB0_508:
	s_or_b64 exec, exec, s[0:1]
	v_cmp_gt_u32_e32 vcc, 0x4000, v131
	v_lshrrev_b32_e32 v238, 3, v131
	v_xor_b32_e32 v238, v238, v131
	v_and_b32_e32 v238, 0x100, v238
	v_lshl_or_b32 v238, v238, 3, v238
	v_cndmask_b32_e32 v238, 0, v238, vcc
	v_xor_b32_e32 v131, v131, v238
	v_cmp_gt_u32_e32 vcc, 0x4000, v133
	v_lshrrev_b32_e32 v238, 3, v133
	v_xor_b32_e32 v238, v238, v133
	v_and_b32_e32 v238, 0x100, v238
	v_lshl_or_b32 v238, v238, 3, v238
	v_cndmask_b32_e32 v238, 0, v238, vcc
	v_xor_b32_e32 v133, v133, v238
	s_lshl_b32 s0, s21, 8
	s_add_u32 s0, s17, s0
	s_addc_u32 s1, s18, 0
	s_and_b32 s23, s12, 0xffffff00
	v_and_b32_e32 v18, 24, v18
	s_add_i32 s10, s23, 0x8000
	v_bfe_u32 v144, v28, 2, 6
	v_lshlrev_b32_e32 v78, 1, v18
	v_lshlrev_b32_e32 v20, 2, v28
	v_lshlrev_b32_e32 v19, 8, v144
	v_or_b32_e32 v18, 0x80, v78
	v_and_b32_e32 v20, 0xf0, v20
	s_ashr_i32 s11, s10, 31
	v_ashrrev_i32_e32 v135, 31, v134
	v_bitop3_b32 v145, v18, v19, v20 bitop3:0xde
	v_lshl_add_u64 v[18:19], v[134:135], 0, s[10:11]
	v_lshlrev_b64 v[18:19], 11, v[18:19]
	v_lshl_add_u64 v[18:19], s[0:1], 0, v[18:19]
	v_lshl_add_u64 v[18:19], v[18:19], 0, v[0:1]
	v_lshl_add_u64 v[136:137], v[134:135], 0, 32
	global_load_dwordx4 v[20:23], v[18:19], off
	v_lshl_add_u64 v[18:19], v[136:137], 0, s[10:11]
	v_lshlrev_b64 v[18:19], 11, v[18:19]
	v_lshl_add_u64 v[18:19], s[0:1], 0, v[18:19]
	v_lshl_add_u64 v[18:19], v[18:19], 0, v[0:1]
	global_load_dwordx4 v[24:27], v[18:19], off
	v_or_b32_e32 v18, s10, v144
	v_mov_b32_e32 v19, s11
	v_lshlrev_b64 v[18:19], 6, v[18:19]
	v_lshl_add_u64 v[18:19], s[6:7], 0, v[18:19]
	v_mov_b32_e32 v79, v1
	s_add_i32 s4, s23, 0x8040
	v_lshl_add_u64 v[18:19], v[18:19], 0, v[78:79]
	s_ashr_i32 s5, s4, 31
	global_load_dwordx4 v[30:33], v[18:19], off
	v_lshl_add_u64 v[18:19], v[134:135], 0, s[4:5]
	v_lshlrev_b64 v[18:19], 11, v[18:19]
	v_lshl_add_u64 v[18:19], s[0:1], 0, v[18:19]
	v_lshl_add_u64 v[18:19], v[18:19], 0, v[0:1]
	global_load_dwordx4 v[66:69], v[18:19], off
	v_lshl_add_u64 v[18:19], v[136:137], 0, s[4:5]
	v_lshlrev_b64 v[18:19], 11, v[18:19]
	v_lshl_add_u64 v[18:19], s[0:1], 0, v[18:19]
	v_lshl_add_u64 v[18:19], v[18:19], 0, v[0:1]
	global_load_dwordx4 v[70:73], v[18:19], off
	v_or_b32_e32 v18, s4, v144
	v_mov_b32_e32 v19, s5
	v_lshlrev_b64 v[18:19], 6, v[18:19]
	v_lshl_add_u64 v[18:19], s[6:7], 0, v[18:19]
	v_lshl_add_u64 v[18:19], v[18:19], 0, v[78:79]
	global_load_dwordx4 v[74:77], v[18:19], off
	s_waitcnt vmcnt(3)
	v_add_u32_e32 v18, 0, v131
	s_movk_i32 s9, 0x80
	v_add_u32_e32 v19, 0, v133
	v_cmp_ne_u32_e64 s[4:5], 1, v207
	s_andn2_b64 vcc, exec, s[54:55]
	s_waitcnt vmcnt(5)
	ds_write_b128 v18, v[20:23]
	v_add_u32_e32 v20, 0, v145
	s_waitcnt vmcnt(4)
	ds_write_b128 v19, v[24:27]
	s_waitcnt vmcnt(3)
	ds_write_b128 v20, v[30:33] offset:49152
	s_cbranch_vccnz .LBB0_510
	s_add_i32 s24, s23, 0x8080
	s_waitcnt vmcnt(0)
	s_waitcnt vmcnt(2)
	ds_write_b128 v18, v[66:69] offset:16384
	s_waitcnt vmcnt(1)
	ds_write_b128 v19, v[70:73] offset:16384
	v_add_u32_e32 v18, 0x10000, v20
	s_ashr_i32 s25, s24, 31
	s_waitcnt vmcnt(0)
	ds_write_b128 v18, v[74:77]
	v_lshl_add_u64 v[18:19], v[134:135], 0, s[24:25]
	v_lshlrev_b64 v[18:19], 11, v[18:19]
	v_lshl_add_u64 v[18:19], s[0:1], 0, v[18:19]
	v_lshl_add_u64 v[18:19], v[18:19], 0, v[0:1]
	s_mov_b32 s9, 0x10000
	v_add_co_u32_e32 v20, vcc, s9, v18
	s_movk_i32 s9, 0xc0
	s_nop 0
	v_addc_co_u32_e32 v21, vcc, 0, v19, vcc
	global_load_dwordx4 v[66:69], v[18:19], off
	global_load_dwordx4 v[70:73], v[20:21], off
	v_mov_b32_e32 v19, s25
	v_or_b32_e32 v18, s24, v144
	v_lshlrev_b64 v[18:19], 6, v[18:19]
	v_lshl_add_u64 v[18:19], s[6:7], 0, v[18:19]
	v_lshl_add_u64 v[18:19], v[18:19], 0, v[78:79]
	global_load_dwordx4 v[74:77], v[18:19], off

; __device__ __forceinline__ void softmaxT(f32x16& p0, f32x16& p1, float& mref, f32x16& negm, float& l_reg, float& alpha, bf16x8& pa0, bf16x8& pa1, bf16x8& pa2, bf16x8& pa3) {
;     ...
;   if (__builtin_expect(__all(pmax <= THR2), 1)) { alpha = 1.f; }
;   else { const float dl = __builtin_fmaxf(pmax, 0.f); mref += dl; alpha = __builtin_amdgcn_exp2f(-dl); l_reg *= alpha;
; #pragma unroll
;     for (int r = 0; r < 16; ++r) { p0[r] -= dl; p1[r] -= dl; negm[r] = -mref; }
;     asm volatile("" : "+v"(negm)); }
; #pragma unroll
;   for (int r = 0; r < 16; ++r) { p0[r] = __builtin_amdgcn_exp2f(p0[r]); p1[r] = __builtin_amdgcn_exp2f(p1[r]); }
;   { float s0 = p0[0] + p1[0], s1 = p0[1] + p1[1], s2 = p0[2] + p1[2], s3 = p0[3] + p1[3];
; #pragma unroll
;     for (int r = 4; r < 16; r += 4) { s0 += p0[r] + p1[r]; s1 += p0[r + 1] + p1[r + 1]; s2 += p0[r + 2] + p1[r + 2]; s3 += p0[r + 3] + p1[r + 3]; }
;     l_reg += (s0 + s1) + (s2 + s3); }
;     ...
;   PK4(p0, 0, pa0); PK4(p0, 8, pa1); PK4(p1, 0, pa2); PK4(p1, 8, pa3);
.LBB0_514:
	v_exp_f32_e32 v106, v50
	v_exp_f32_e32 v107, v34
	v_exp_f32_e32 v34, v51
	v_exp_f32_e32 v108, v35
	v_exp_f32_e32 v35, v52
	v_exp_f32_e32 v109, v36
	v_exp_f32_e32 v36, v53
	v_exp_f32_e32 v110, v37
	v_exp_f32_e32 v37, v54
	v_exp_f32_e32 v111, v38
	v_exp_f32_e32 v38, v55
	v_exp_f32_e32 v112, v39
	v_exp_f32_e32 v39, v56
	v_exp_f32_e32 v113, v40
	v_exp_f32_e32 v40, v57
	v_exp_f32_e32 v114, v41
	v_exp_f32_e32 v41, v58
	v_exp_f32_e32 v115, v42
	v_exp_f32_e32 v42, v59
	v_exp_f32_e32 v116, v43
	v_exp_f32_e32 v43, v60
	v_exp_f32_e32 v117, v44
	v_exp_f32_e32 v44, v61
	v_exp_f32_e32 v138, v45
	v_exp_f32_e32 v45, v62
	v_exp_f32_e32 v139, v46
	v_exp_f32_e32 v46, v63
	v_exp_f32_e32 v140, v47
	v_exp_f32_e32 v47, v64
	v_exp_f32_e32 v141, v48
	v_exp_f32_e32 v48, v65
	v_exp_f32_e32 v49, v49
	v_and_b32_e32 v18, 0x3fffffc0, v28
	s_add_i32 s4, 0, 0x18000
	v_lshl_add_u32 v154, v18, 2, s4
	v_cvt_pk_bf16_f32 v54, v106, v34
	v_cvt_pk_bf16_f32 v55, v35, v36
	v_cvt_pk_bf16_f32 v56, v37, v38
	v_cvt_pk_bf16_f32 v57, v39, v40
	v_cvt_pk_bf16_f32 v50, v41, v42
	v_cvt_pk_bf16_f32 v51, v43, v44
	v_cvt_pk_bf16_f32 v52, v45, v46
	v_cvt_pk_bf16_f32 v53, v47, v48
	v_cvt_pk_bf16_f32 v58, v107, v108
	v_cvt_pk_bf16_f32 v59, v109, v110
	v_cvt_pk_bf16_f32 v60, v111, v112
	v_cvt_pk_bf16_f32 v61, v113, v114
	v_cvt_pk_bf16_f32 v62, v115, v116
	v_cvt_pk_bf16_f32 v63, v117, v138
	v_cvt_pk_bf16_f32 v64, v139, v140
	v_cvt_pk_bf16_f32 v65, v141, v49
	v_lshl_add_u32 v155, v142, 2, v154
	v_cmp_gt_f32_e32 vcc, 1.0, v81
	v_mov_b32_e32 v32, 0
	v_mov_b32_e32 v31, 0
	v_mov_b32_e32 v30, 0
	v_mov_b32_e32 v29, 0
	v_mov_b32_e32 v28, 0
	v_mov_b32_e32 v27, 0
	v_mov_b32_e32 v26, 0
	v_mov_b32_e32 v25, 0
	v_mov_b32_e32 v24, 0
	v_mov_b32_e32 v23, 0
	v_mov_b32_e32 v22, 0
	v_mov_b32_e32 v21, 0
	v_mov_b32_e32 v20, 0
	v_mov_b32_e32 v19, 0
	v_mov_b32_e32 v18, 0
	s_cbranch_vccz .LBB0_518
	s_and_saveexec_b64 s[4:5], s[2:3]
	ds_write_b32 v155, v81
	s_or_b64 exec, exec, s[4:5]
	s_waitcnt lgkmcnt(0)
	v_add_u32_e32 v26, v154, v132
	ds_read_b128 v[18:21], v26 offset:96
	ds_read_b128 v[22:25], v26 offset:64
	ds_read_b128 v[156:159], v26 offset:32
	ds_read_b128 v[160:163], v26
	s_waitcnt lgkmcnt(3)
	v_pk_mul_f32 v[32:33], v[20:21], 0 op_sel_hi:[1,0]
	s_waitcnt lgkmcnt(2)
	v_pk_mul_f32 v[28:29], v[24:25], 0 op_sel_hi:[1,0]
	s_waitcnt lgkmcnt(1)
	v_pk_mul_f32 v[24:25], v[158:159], 0 op_sel_hi:[1,0]
	s_waitcnt lgkmcnt(0)
	v_pk_mul_f32 v[20:21], v[162:163], 0 op_sel_hi:[1,0]
	v_pk_mul_f32 v[30:31], v[18:19], 0 op_sel_hi:[1,0]
	v_pk_mul_f32 v[26:27], v[22:23], 0 op_sel_hi:[1,0]
	v_pk_mul_f32 v[22:23], v[156:157], 0 op_sel_hi:[1,0]
	v_pk_mul_f32 v[18:19], v[160:161], 0 op_sel_hi:[1,0]

; __device__ __forceinline__ void softmaxT(f32x16& p0, f32x16& p1, float& mref, f32x16& negm, float& l_reg, float& alpha, bf16x8& pa0, bf16x8& pa1, bf16x8& pa2, bf16x8& pa3) {
;     ...
;   for (int r = 0; r < 16; ++r) { p0[r] = __builtin_amdgcn_exp2f(p0[r]); p1[r] = __builtin_amdgcn_exp2f(p1[r]); }
;   { float s0 = p0[0] + p1[0], s1 = p0[1] + p1[1], s2 = p0[2] + p1[2], s3 = p0[3] + p1[3];
; #pragma unroll
;     for (int r = 4; r < 16; r += 4) { s0 += p0[r] + p1[r]; s1 += p0[r + 1] + p1[r + 1]; s2 += p0[r + 2] + p1[r + 2]; s3 += p0[r + 3] + p1[r + 3]; }
;     l_reg += (s0 + s1) + (s2 + s3); }
;     ...
;   PK4(p0, 0, pa0); PK4(p0, 8, pa1); PK4(p1, 0, pa2); PK4(p1, 8, pa3);
.LBB0_519:
	v_exp_f32_e32 v66, v66
	v_exp_f32_e32 v159, v50
	v_exp_f32_e32 v67, v67
	v_exp_f32_e32 v160, v51
	v_exp_f32_e32 v68, v68
	v_exp_f32_e32 v161, v52
	v_exp_f32_e32 v69, v69
	v_exp_f32_e32 v178, v53
	v_exp_f32_e32 v70, v70
	v_exp_f32_e32 v179, v54
	v_exp_f32_e32 v71, v71
	v_exp_f32_e32 v180, v55
	v_exp_f32_e32 v72, v72
	v_exp_f32_e32 v181, v56
	v_exp_f32_e32 v73, v73
	v_exp_f32_e32 v182, v57
	v_exp_f32_e32 v74, v74
	v_exp_f32_e32 v183, v58
	v_exp_f32_e32 v75, v75
	v_exp_f32_e32 v184, v59
	v_exp_f32_e32 v76, v76
	v_exp_f32_e32 v185, v60
	v_exp_f32_e32 v77, v77
	v_exp_f32_e32 v186, v61
	v_exp_f32_e32 v78, v78
	v_exp_f32_e32 v187, v62
	v_exp_f32_e32 v79, v79
	v_exp_f32_e32 v188, v63
	v_exp_f32_e32 v80, v80
	v_exp_f32_e32 v189, v64
	v_exp_f32_e32 v81, v81
	v_exp_f32_e32 v190, v65
	v_cvt_pk_bf16_f32 v62, v66, v67
	v_cvt_pk_bf16_f32 v63, v68, v69
	v_cvt_pk_bf16_f32 v64, v70, v71
	v_cvt_pk_bf16_f32 v65, v72, v73
	v_cvt_pk_bf16_f32 v50, v74, v75
	v_cvt_pk_bf16_f32 v51, v76, v77
	v_cvt_pk_bf16_f32 v52, v78, v79
	v_cvt_pk_bf16_f32 v53, v80, v81
	v_cvt_pk_bf16_f32 v54, v159, v160
	v_cvt_pk_bf16_f32 v55, v161, v178
	v_cvt_pk_bf16_f32 v56, v179, v180
	v_cvt_pk_bf16_f32 v57, v181, v182
	v_cvt_pk_bf16_f32 v58, v183, v184
	v_cvt_pk_bf16_f32 v59, v185, v186
	v_cvt_pk_bf16_f32 v60, v187, v188
	v_cvt_pk_bf16_f32 v61, v189, v190
	v_cmp_gt_f32_e32 vcc, 1.0, v158
	s_cbranch_vccz .LBB0_523
	s_and_saveexec_b64 s[0:1], s[2:3]
	ds_write_b32 v155, v158
	s_or_b64 exec, exec, s[0:1]
	s_waitcnt lgkmcnt(0)
	v_add_u32_e32 v158, v154, v132
	ds_read_b128 v[162:165], v158 offset:96
	ds_read_b128 v[166:169], v158 offset:64
	ds_read_b128 v[170:173], v158 offset:32
	ds_read_b128 v[192:195], v158
	s_waitcnt lgkmcnt(3)
	v_pk_mul_f32 v[46:47], v[46:47], v[162:163]
	s_waitcnt lgkmcnt(2)
	v_pk_mul_f32 v[42:43], v[42:43], v[166:167]
	s_waitcnt lgkmcnt(1)
	v_pk_mul_f32 v[38:39], v[38:39], v[170:171]
	v_pk_mul_f32 v[48:49], v[48:49], v[164:165]
	v_pk_mul_f32 v[44:45], v[44:45], v[168:169]
	v_pk_mul_f32 v[40:41], v[40:41], v[172:173]
	s_waitcnt lgkmcnt(0)
	v_pk_mul_f32 v[36:37], v[36:37], v[194:195]
	v_pk_mul_f32 v[34:35], v[34:35], v[192:193]
	v_pk_mul_f32 v[30:31], v[30:31], v[162:163]
	v_pk_mul_f32 v[26:27], v[26:27], v[166:167]
	v_pk_mul_f32 v[22:23], v[22:23], v[170:171]
	v_pk_mul_f32 v[32:33], v[32:33], v[164:165]
	v_pk_mul_f32 v[28:29], v[28:29], v[168:169]
	v_pk_mul_f32 v[24:25], v[24:25], v[172:173]
	v_pk_mul_f32 v[20:21], v[20:21], v[194:195]
	v_pk_mul_f32 v[18:19], v[18:19], v[192:193]

; __device__ __forceinline__ void softmaxT(f32x16& p0, f32x16& p1, float& mref, f32x16& negm, float& l_reg, float& alpha, bf16x8& pa0, bf16x8& pa1, bf16x8& pa2, bf16x8& pa3) {
;     ...
;   for (int r = 0; r < 16; ++r) { p0[r] = __builtin_amdgcn_exp2f(p0[r]); p1[r] = __builtin_amdgcn_exp2f(p1[r]); }
;   { float s0 = p0[0] + p1[0], s1 = p0[1] + p1[1], s2 = p0[2] + p1[2], s3 = p0[3] + p1[3];
; #pragma unroll
;     for (int r = 4; r < 16; r += 4) { s0 += p0[r] + p1[r]; s1 += p0[r + 1] + p1[r + 1]; s2 += p0[r + 2] + p1[r + 2]; s3 += p0[r + 3] + p1[r + 3]; }
;     l_reg += (s0 + s1) + (s2 + s3); }
;     ...
;   PK4(p0, 0, pa0); PK4(p0, 8, pa1); PK4(p1, 0, pa2); PK4(p1, 8, pa3);
.LBB0_525:
	v_exp_f32_e32 v66, v66
	v_exp_f32_e32 v222, v50
	v_exp_f32_e32 v67, v67
	v_exp_f32_e32 v223, v51
	v_exp_f32_e32 v68, v68
	v_exp_f32_e32 v224, v52
	v_exp_f32_e32 v69, v69
	v_exp_f32_e32 v225, v53
	v_exp_f32_e32 v70, v70
	v_exp_f32_e32 v226, v54
	v_exp_f32_e32 v71, v71
	v_exp_f32_e32 v227, v55
	v_exp_f32_e32 v72, v72
	v_exp_f32_e32 v228, v56
	v_exp_f32_e32 v73, v73
	v_exp_f32_e32 v229, v57
	v_exp_f32_e32 v74, v74
	v_exp_f32_e32 v230, v58
	v_exp_f32_e32 v75, v75
	v_exp_f32_e32 v231, v59
	v_exp_f32_e32 v76, v76
	v_exp_f32_e32 v232, v60
	v_exp_f32_e32 v77, v77
	v_exp_f32_e32 v233, v61
	v_exp_f32_e32 v78, v78
	v_exp_f32_e32 v234, v62
	v_exp_f32_e32 v79, v79
	v_exp_f32_e32 v235, v63
	v_exp_f32_e32 v80, v80
	v_exp_f32_e32 v236, v64
	v_exp_f32_e32 v81, v81
	v_exp_f32_e32 v237, v65
	v_cvt_pk_bf16_f32 v54, v66, v67
	v_cvt_pk_bf16_f32 v55, v68, v69
	v_cvt_pk_bf16_f32 v56, v70, v71
	v_cvt_pk_bf16_f32 v57, v72, v73
	v_cvt_pk_bf16_f32 v50, v74, v75
	v_cvt_pk_bf16_f32 v51, v76, v77
	v_cvt_pk_bf16_f32 v52, v78, v79
	v_cvt_pk_bf16_f32 v53, v80, v81
	v_cvt_pk_bf16_f32 v58, v222, v223
	v_cvt_pk_bf16_f32 v59, v224, v225
	v_cvt_pk_bf16_f32 v60, v226, v227
	v_cvt_pk_bf16_f32 v61, v228, v229
	v_cvt_pk_bf16_f32 v62, v230, v231
	v_cvt_pk_bf16_f32 v63, v232, v233
	v_cvt_pk_bf16_f32 v64, v234, v235
	v_cvt_pk_bf16_f32 v65, v236, v237
	v_cmp_gt_f32_e32 vcc, 1.0, v158
	s_cbranch_vccz .LBB0_529
	s_and_saveexec_b64 s[0:1], s[2:3]
	ds_write_b32 v155, v158
	s_or_b64 exec, exec, s[0:1]
	s_waitcnt lgkmcnt(0)
	v_add_u32_e32 v158, v154, v132
	ds_read_b128 v[162:165], v158 offset:96
	ds_read_b128 v[166:169], v158 offset:64
	ds_read_b128 v[170:173], v158 offset:32
	ds_read_b128 v[192:195], v158
	s_waitcnt lgkmcnt(3)
	v_pk_mul_f32 v[46:47], v[46:47], v[162:163]
	s_waitcnt lgkmcnt(2)
	v_pk_mul_f32 v[42:43], v[42:43], v[166:167]
	s_waitcnt lgkmcnt(1)
	v_pk_mul_f32 v[38:39], v[38:39], v[170:171]
	v_pk_mul_f32 v[48:49], v[48:49], v[164:165]
	v_pk_mul_f32 v[44:45], v[44:45], v[168:169]
	v_pk_mul_f32 v[40:41], v[40:41], v[172:173]
	s_waitcnt lgkmcnt(0)
	v_pk_mul_f32 v[36:37], v[36:37], v[194:195]
	v_pk_mul_f32 v[34:35], v[34:35], v[192:193]
	v_pk_mul_f32 v[30:31], v[30:31], v[162:163]
	v_pk_mul_f32 v[26:27], v[26:27], v[166:167]
	v_pk_mul_f32 v[22:23], v[22:23], v[170:171]
	v_pk_mul_f32 v[32:33], v[32:33], v[164:165]
	v_pk_mul_f32 v[28:29], v[28:29], v[168:169]
	v_pk_mul_f32 v[24:25], v[24:25], v[172:173]
	v_pk_mul_f32 v[20:21], v[20:21], v[194:195]
	v_pk_mul_f32 v[18:19], v[18:19], v[192:193]

; __device__ __forceinline__ void softmaxT(f32x16& p0, f32x16& p1, float& mref, f32x16& negm, float& l_reg, float& alpha, bf16x8& pa0, bf16x8& pa1, bf16x8& pa2, bf16x8& pa3) {
;     ...
;   for (int r = 0; r < 16; ++r) { p0[r] = __builtin_amdgcn_exp2f(p0[r]); p1[r] = __builtin_amdgcn_exp2f(p1[r]); }
;   { float s0 = p0[0] + p1[0], s1 = p0[1] + p1[1], s2 = p0[2] + p1[2], s3 = p0[3] + p1[3];
; #pragma unroll
;     for (int r = 4; r < 16; r += 4) { s0 += p0[r] + p1[r]; s1 += p0[r + 1] + p1[r + 1]; s2 += p0[r + 2] + p1[r + 2]; s3 += p0[r + 3] + p1[r + 3]; }
;     l_reg += (s0 + s1) + (s2 + s3); }
;     ...
;   PK4(p0, 0, pa0); PK4(p0, 8, pa1); PK4(p1, 0, pa2); PK4(p1, 8, pa3);
.LBB0_532:
	v_exp_f32_e32 v66, v66
	v_exp_f32_e32 v222, v50
	v_exp_f32_e32 v67, v67
	v_exp_f32_e32 v223, v51
	v_exp_f32_e32 v68, v68
	v_exp_f32_e32 v224, v52
	v_exp_f32_e32 v69, v69
	v_exp_f32_e32 v225, v53
	v_exp_f32_e32 v70, v70
	v_exp_f32_e32 v226, v54
	v_exp_f32_e32 v71, v71
	v_exp_f32_e32 v227, v55
	v_exp_f32_e32 v72, v72
	v_exp_f32_e32 v228, v56
	v_exp_f32_e32 v73, v73
	v_exp_f32_e32 v229, v57
	v_exp_f32_e32 v74, v74
	v_exp_f32_e32 v230, v58
	v_exp_f32_e32 v75, v75
	v_exp_f32_e32 v231, v59
	v_exp_f32_e32 v76, v76
	v_exp_f32_e32 v232, v60
	v_exp_f32_e32 v77, v77
	v_exp_f32_e32 v233, v61
	v_exp_f32_e32 v78, v78
	v_exp_f32_e32 v234, v62
	v_exp_f32_e32 v79, v79
	v_exp_f32_e32 v235, v63
	v_exp_f32_e32 v80, v80
	v_exp_f32_e32 v236, v64
	v_exp_f32_e32 v81, v81
	v_exp_f32_e32 v237, v65
	v_cvt_pk_bf16_f32 v62, v66, v67
	v_cvt_pk_bf16_f32 v63, v68, v69
	v_cvt_pk_bf16_f32 v64, v70, v71
	v_cvt_pk_bf16_f32 v65, v72, v73
	v_cvt_pk_bf16_f32 v50, v74, v75
	v_cvt_pk_bf16_f32 v51, v76, v77
	v_cvt_pk_bf16_f32 v52, v78, v79
	v_cvt_pk_bf16_f32 v53, v80, v81
	v_cvt_pk_bf16_f32 v54, v222, v223
	v_cvt_pk_bf16_f32 v55, v224, v225
	v_cvt_pk_bf16_f32 v56, v226, v227
	v_cvt_pk_bf16_f32 v57, v228, v229
	v_cvt_pk_bf16_f32 v58, v230, v231
	v_cvt_pk_bf16_f32 v59, v232, v233
	v_cvt_pk_bf16_f32 v60, v234, v235
	v_cvt_pk_bf16_f32 v61, v236, v237
	v_cmp_gt_f32_e32 vcc, 1.0, v158
	s_cbranch_vccz .LBB0_536
	s_and_saveexec_b64 s[0:1], s[2:3]
	ds_write_b32 v155, v158
	s_or_b64 exec, exec, s[0:1]
	s_waitcnt lgkmcnt(0)
	v_add_u32_e32 v158, v154, v132
	ds_read_b128 v[162:165], v158 offset:96
	ds_read_b128 v[166:169], v158 offset:64
	ds_read_b128 v[170:173], v158 offset:32
	ds_read_b128 v[192:195], v158
	s_waitcnt lgkmcnt(3)
	v_pk_mul_f32 v[46:47], v[46:47], v[162:163]
	s_waitcnt lgkmcnt(2)
	v_pk_mul_f32 v[42:43], v[42:43], v[166:167]
	s_waitcnt lgkmcnt(1)
	v_pk_mul_f32 v[38:39], v[38:39], v[170:171]
	v_pk_mul_f32 v[48:49], v[48:49], v[164:165]
	v_pk_mul_f32 v[44:45], v[44:45], v[168:169]
	v_pk_mul_f32 v[40:41], v[40:41], v[172:173]
	s_waitcnt lgkmcnt(0)
	v_pk_mul_f32 v[36:37], v[36:37], v[194:195]
	v_pk_mul_f32 v[34:35], v[34:35], v[192:193]
	v_pk_mul_f32 v[30:31], v[30:31], v[162:163]
	v_pk_mul_f32 v[26:27], v[26:27], v[166:167]
	v_pk_mul_f32 v[22:23], v[22:23], v[170:171]
	v_pk_mul_f32 v[32:33], v[32:33], v[164:165]
	v_pk_mul_f32 v[28:29], v[28:29], v[168:169]
	v_pk_mul_f32 v[24:25], v[24:25], v[172:173]
	v_pk_mul_f32 v[20:21], v[20:21], v[194:195]
	v_pk_mul_f32 v[18:19], v[18:19], v[192:193]
